# stage3 units panel-aligned; barrier stage3->out-proj narrowed to the 4-workgroup panel group with a batch-wide stage3-done count checked before the H stores
# speedup vs baseline: 1.0276x; 1.0014x over previous
; __global__ void __launch_bounds__(512) hymba_fwd(Args a) {
;     ...
;                 { PrepIn cur; int u = wb; moba_prep_load(a, tid, u < 512 ? u : 0, cur);
;                   for (; u < 512; u += WG) { PrepIn nxt; moba_prep_unit(a, l, lds, tid, u, cur, nxt, (u + WG < 512) ? u + WG : u); cur = nxt; } }
;                 { HIn cur; int u = (wb + 160) % WG;     hgrn_load<false>(a, tid, u < 1024 ? u : 0, cur);
;     ...
;               HIn cur; int u = bx; hgrn_load<true>(a, tid, u < 1024 ? u : 0, cur);
;                 for (; u < 1024; u += G) { HIn nxt; hgrn_stage3_unit(a, l, lds, tid, u, cur, nxt, (u + G < 1024) ? u + G : u); cur = nxt; } }
.Lrm_wb:
	s_sub_i32 s17, s3, s1
	v_writelane_b32 v245, s9, 29
	s_add_u32 s8, s78, 0xfb00000
	s_addc_u32 s9, s79, 0
	v_writelane_b32 v245, s8, 30
	s_cmpk_lt_i32 s10, 0x200
	s_nop 0
	v_writelane_b32 v245, s9, 31
	s_cselect_b64 s[8:9], -1, 0
	v_writelane_b32 v245, s8, 32
	s_nop 1
	v_writelane_b32 v245, s9, 33
	s_and_b64 s[8:9], s[8:9], exec
	s_cselect_b32 s1, s10, 0
	s_ashr_i32 s8, s1, 6
	s_ashr_i32 s9, s8, 31
	s_and_b32 s6, s1, 7
	s_lshl_b64 s[12:13], s[8:9], 11
	s_lshl_b32 s1, s1, 5
	v_writelane_b32 v245, s12, 34
	s_and_b32 s14, s1, 0x700
	s_lshl_b32 s1, s6, 7
	v_writelane_b32 v245, s13, 35
	s_add_u32 s12, s84, s1
	s_addc_u32 s13, s85, 0
	s_lshl_b32 s1, s8, 3
	s_or_b32 s8, s1, s6
	s_ashr_i32 s9, s8, 31
	s_lshl_b64 s[8:9], s[8:9], 18
	v_writelane_b32 v245, s12, 36
	s_add_u32 s8, s33, s8
	s_addc_u32 s9, s20, s9
	v_writelane_b32 v245, s13, 37
	v_writelane_b32 v245, s8, 38
	s_mov_b64 s[12:13], 0x1000
	s_nop 0
	v_writelane_b32 v245, s9, 39
	s_add_u32 s8, s78, 0xf700000
	s_addc_u32 s9, s79, 0
	v_writelane_b32 v245, s8, 40
	s_add_u32 s1, s78, 0xf600000
	s_nop 0
	v_writelane_b32 v245, s9, 41
	v_writelane_b32 v245, s1, 42
	s_addc_u32 s1, s79, 0
	v_writelane_b32 v245, s1, 43
	s_add_i32 s1, s10, 0xa0
	v_writelane_b32 v245, s10, 44
	s_add_u32 s6, s78, 0xf620000
	v_writelane_b32 v245, s6, 45
	s_addc_u32 s6, s79, 0
	s_cmpk_lt_i32 s2, 0x200
	v_writelane_b32 v245, s6, 46
	s_cselect_b64 s[8:9], -1, 0
	v_writelane_b32 v245, s8, 47
	s_lshl_b32 s6, s2, 5
	s_and_b32 s6, s6, 0xe0
	v_writelane_b32 v245, s9, 48
	s_ashr_i32 s8, s2, 3
	s_add_i32 s6, s6, s8
	s_ashr_i32 s6, s6, 2
	v_writelane_b32 v245, s6, 49
	s_and_b32 s6, s8, 3
	v_writelane_b32 v245, s6, 50
	s_xor_b32 s6, s6, 7
	s_cmpk_lt_i32 s2, 0x100
	v_writelane_b32 v245, s6, 51
	s_cselect_b64 s[8:9], -1, 0
	v_writelane_b32 v245, s8, 52
	s_lshl_b32 s6, s2, 9
	s_nop 0
	v_writelane_b32 v245, s9, 53
	v_writelane_b32 v245, s6, 54
	s_lshl_b32 s6, s3, 9
	s_cmpk_lt_i32 s2, 0x400
	v_writelane_b32 v245, s6, 55
	s_cselect_b64 s[8:9], -1, 0
	v_writelane_b32 v245, s8, 56
	s_nop 1
	v_writelane_b32 v245, s9, 57
	s_and_b64 s[8:9], s[8:9], exec
	s_cselect_b32 s6, s2, 0
	s_cmp_eq_u32 s3, 0x100
	s_cbranch_scc0 .Lrm_s3a
	s_and_b32 s6, s2, 7
	s_lshl_b32 s6, s6, 7
	s_bfe_u32 s8, s2, 0x30003
	s_lshl_b32 s8, s8, 2
	s_or_b32 s6, s6, s8
	s_lshr_b32 s8, s2, 6
	s_or_b32 s6, s6, s8

; #define LAS __attribute__((address_space(3)))
; __device__ __forceinline__ int otid() { int t = threadIdx.x; asm volatile("" : "+v"(t)); return t; }
; __global__ void __launch_bounds__(512) hymba_fwd(Args a) {
;     ...
;             { const int tid = otid();
;               if (tid < 512) ((LAS float*)(lds + 106496))[tid] = ((const float*)(a.ws + WS_LB))[l * 512 + tid];
;               if (tid < 128) ((LAS float*)(lds + 106496 + 2048))[tid] = a.hon[l * 128 + tid];
;               __syncthreads();
;               HIn cur; int u = bx; hgrn_load<true>(a, tid, u < 1024 ? u : 0, cur);
;                 for (; u < 1024; u += G) { HIn nxt; hgrn_stage3_unit(a, l, lds, tid, u, cur, nxt, (u + G < 1024) ? u + G : u); cur = nxt; } }
.LBB0_641:
	s_or_b64 exec, exec, s[14:15]
	v_readlane_b32 s4, v245, 56
	v_readlane_b32 s5, v245, 57
	s_andn2_b64 vcc, exec, s[4:5]
	s_waitcnt lgkmcnt(0)
	s_barrier
	s_cbranch_vccnz .LBB0_680
	v_add_u32_e32 v0, 0x200, v121
	v_ashrrev_i32_e32 v118, 4, v0
	v_readlane_b32 s4, v245, 58
	v_ashrrev_i32_e32 v119, 31, v118
	v_readlane_b32 s5, v245, 59
	v_lshlrev_b32_e32 v9, 3, v121
	v_ashrrev_i32_e32 v116, 4, v121
	v_lshl_add_u64 v[0:1], s[4:5], 0, v[118:119]
	v_readlane_b32 s8, v245, 60
	v_and_b32_e32 v8, 0x78, v9
	v_ashrrev_i32_e32 v117, 31, v116
	v_lshlrev_b64 v[0:1], 13, v[0:1]
	v_readlane_b32 s9, v245, 61
	v_lshlrev_b32_e32 v144, 1, v8
	v_lshl_add_u64 v[6:7], s[4:5], 0, v[116:117]
	v_lshl_add_u64 v[0:1], s[8:9], 0, v[0:1]
	v_lshl_add_u64 v[0:1], v[0:1], 0, v[144:145]
	v_lshlrev_b64 v[6:7], 13, v[6:7]
	v_add_co_u32_e32 v4, vcc, s26, v0
	v_lshl_add_u64 v[6:7], s[8:9], 0, v[6:7]
	s_nop 0
	v_addc_co_u32_e32 v5, vcc, 0, v1, vcc
	v_lshl_add_u64 v[6:7], v[6:7], 0, v[144:145]
	global_load_dwordx4 v[28:31], v[0:1], off offset:1024
	s_nop 0
	global_load_dwordx4 v[0:3], v[4:5], off offset:2048
	global_load_dwordx4 v[24:27], v[4:5], off offset:3072
	global_load_dwordx4 v[100:103], v[6:7], off offset:1024
	v_add_co_u32_e32 v4, vcc, s26, v6
	v_bfe_u32 v11, v121, 4, 2
	s_nop 0
	v_addc_co_u32_e32 v5, vcc, 0, v7, vcc
	global_load_dwordx4 v[72:75], v[4:5], off offset:3072
	s_nop 0
	global_load_dwordx4 v[4:7], v[4:5], off offset:2048
	v_lshlrev_b32_e32 v122, 2, v11
	s_add_i32 s4, 0, 0x1a000
	v_lshlrev_b32_e32 v10, 2, v8
	v_and_b32_e32 v120, 15, v121
	v_or_b32_e32 v32, 2, v122
	v_add_u32_e32 v170, s4, v10
	v_add_u32_e32 v171, 0, v10
	v_lshlrev_b32_e32 v10, 5, v121
	v_and_b32_e32 v12, 0x7f, v121
	v_readlane_b32 s4, v244, 53
	v_cmp_gt_u32_e64 s[52:53], v32, v120
	v_or_b32_e32 v32, 3, v122
	v_and_b32_e32 v10, 0xfffffe00, v10
	v_ashrrev_i32_e32 v13, 7, v121
	v_lshl_add_u32 v174, v12, 2, 0
	v_readlane_b32 s5, v244, 54
	v_lshlrev_b32_e32 v17, 4, v11
	v_mov_b32_e32 v21, s4
	v_cmp_gt_u32_e64 s[54:55], v32, v120
	v_bfe_u32 v32, v121, 2, 2
	v_add_u32_e32 v172, v171, v10
	v_lshlrev_b32_e32 v10, 3, v11
	v_lshl_add_u32 v175, v13, 13, v174
	v_cmp_lt_i32_e64 s[42:43], 0, v13
	v_cmp_lt_i32_e64 s[44:45], 1, v13
	v_cmp_lt_i32_e64 s[46:47], 2, v13
	v_add_u32_e32 v177, s4, v144
	v_add_u32_e32 v12, s5, v144
	v_lshlrev_b32_e32 v13, 9, v116
	v_mul_lo_u32 v14, v116, s27
	v_lshlrev_b32_e32 v15, 9, v118
	v_mul_lo_u32 v16, v118, s27
	v_add_u32_e32 v18, s4, v17
	v_mul_u32_u24_e32 v19, 0x110, v120
	v_or_b32_e32 v20, 64, v17
	v_mad_u32_u24 v21, v120, s31, v21
	v_or_b32_e32 v22, 0x80, v17
	v_or_b32_e32 v23, 0xc0, v17
	v_and_b32_e32 v182, 24, v9
	v_or_b32_e32 v9, v122, v32
	v_mov_b32_e32 v32, s5
	v_readlane_b32 s4, v244, 55
	v_lshlrev_b32_e32 v173, 7, v120
	v_sub_u32_e32 v176, v171, v144
	v_mul_lo_u32 v180, v116, s31
	v_mul_lo_u32 v181, v118, s31
	v_cmp_gt_u32_e64 s[48:49], v122, v120
	v_cmp_ge_u32_e64 s[50:51], v122, v120
	v_mad_u32_u24 v183, v9, s27, v32
	v_add_u32_e32 v195, 0, v17
	v_cmp_eq_u32_e64 s[56:57], 0, v11
	v_lshl_add_u32 v196, v120, 2, s4
	v_lshlrev_b32_e32 v144, 1, v10
	v_lshlrev_b32_e32 v124, 1, v8
	v_add_u32_e32 v197, v171, v13
	v_add_u32_e32 v198, v12, v14
	v_add_u32_e32 v199, v171, v15
	v_add_u32_e32 v200, v12, v16
	v_add_u32_e32 v201, v18, v19
	v_add_u32_e32 v202, v21, v20
	v_add_u32_e32 v203, v21, v22
	v_add_u32_e32 v204, v21, v23
	s_mov_b32 s8, s2
	s_mov_b32 s98, s3
	s_movk_i32 s99, 0x400
	s_cmp_eq_u32 s3, 0x100
	s_cbranch_scc0 .Lrm_s3
	s_and_b32 s8, s2, 7
	s_lshl_b32 s8, s8, 7
	s_add_i32 s99, s8, 0x80
	s_bfe_u32 s98, s2, 0x30003
	s_lshl_b32 s98, s98, 2
	s_or_b32 s8, s8, s98
	s_lshr_b32 s98, s2, 6
	s_or_b32 s8, s8, s98
	s_mov_b32 s98, 32

; #define LAS __attribute__((address_space(3)))
; __device__ __forceinline__ unsigned cvt_pk_bf16(float lo, float hi) { unsigned r; asm volatile("v_cvt_pk_bf16_f32 %0, %1, %2" : "=v"(r) : "v"(lo), "v"(hi)); return r; }
;     __device__ __forceinline__ void operator()(const f32x4 (&acc)[2][2][4][2], const Unit& u, int wr, int wc, int fr, int fq, LAS unsigned char* lds) const {
;         const int row0 = u.pm * BM + wr * 64 + fr; const int col0 = u.pn * BM + wc * 32 + 8 * fq;
;         LAS float* part = (LAS float*)(lds + 131072);
;         f32x4 gg[2][2];
; #pragma unroll
;         for (int bj = 0; bj < 2; ++bj)
; #pragma unroll
;             for (int n = 0; n < 2; ++n) gg[bj][n] = *(const f32x4*)(g + col0 + bj * HALF + 4 * n);
; #pragma unroll
;         for (int ai = 0; ai < 2; ++ai)
; #pragma unroll
;             for (int m = 0; m < 4; ++m) { const size_t ro = (size_t)(row0 + ai * HALF + m * 16) * ldc + col0; float ssq = 0.f;
; #pragma unroll
;                 for (int bj = 0; bj < 2; ++bj) { const size_t o = ro + bj * HALF;
;                     const f32x4 r0 = *(const f32x4*)(res + o), r1 = *(const f32x4*)(res + o + 4);
;                     const f32x4 x0 = r0 + acc[ai][bj][m][0], x1 = r1 + acc[ai][bj][m][1];
;                     *(f32x4*)(O + o) = x0; *(f32x4*)(O + o + 4) = x1;
;                     u32x4 hb; hb.x = cvt_pk_bf16(x0[0] * gg[bj][0][0], x0[1] * gg[bj][0][1]); hb.y = cvt_pk_bf16(x0[2] * gg[bj][0][2], x0[3] * gg[bj][0][3]);
;                     hb.z = cvt_pk_bf16(x1[0] * gg[bj][1][0], x1[1] * gg[bj][1][1]); hb.w = cvt_pk_bf16(x1[2] * gg[bj][1][2], x1[3] * gg[bj][1][3]);
;                     *(u32x4*)(H + o) = hb;
;                     ssq += ((x0[0] * x0[0] + x0[1] * x0[1]) + (x0[2] * x0[2] + x0[3] * x0[3])) + ((x1[0] * x1[0] + x1[1] * x1[1]) + (x1[2] * x1[2] + x1[3] * x1[3])); }
;                 ssq += __shfl_xor(ssq, 16); ssq += __shfl_xor(ssq, 32);
.LBB0_786:
	s_cmp_eq_u32 s3, 0x100
	s_cbranch_scc0 .Lb3_skip
	s_add_u32 s16, s78, 0xfc00000
	s_addc_u32 s17, s79, 0
	s_and_b32 s18, s2, 7
	s_lshl_b32 s18, s18, 6
	v_cmp_eq_u32_e32 vcc, 0, v178
	s_and_saveexec_b64 s[14:15], vcc
	s_cbranch_execz .Lb3_join
	v_mov_b32_e32 v24, s18
	s_mov_b32 s5, 0
.Lb3_spin:
	global_load_dword v25, v24, s[16:17] offset:8 sc1
	s_waitcnt vmcnt(0)
	v_readfirstlane_b32 s19, v25
	s_cmp_ge_u32 s19, 32
	s_cbranch_scc1 .Lb3_join
	s_add_i32 s5, s5, 1
	s_cmp_lt_u32 s5, 0x40000
	s_cbranch_scc1 .Lb3_spin
.Lb3_join:
	s_or_b64 exec, exec, s[14:15]
	s_barrier
.Lb3_skip:
	s_lshl_b32 s46, s4, 8
	v_readlane_b32 s4, v244, 0
	v_readlane_b32 s5, v244, 1
	v_and_b32_e32 v25, 8, v172
	v_sub_u32_e32 v26, v172, v25
	v_add_u32_e32 v26, s46, v26
	v_lshl_or_b32 v27, s56, 8, v174
	v_lshrrev_b32_e32 v25, 1, v25
	v_add_u32_e32 v27, v27, v25
	v_lshl_add_u32 v28, v26, 10, v27
	v_lshlrev_b32_e32 v170, 2, v28
	v_lshlrev_b32_e32 v247, 1, v28
	v_lshlrev_b32_e32 v27, 2, v27
	v_add_u32_e32 v171, 0x8000, v170
	v_add_u32_e32 v24, 0x4000, v247
	v_mov_b32_e32 v177, v170
	v_mov_b32_e32 v195, v171
	v_lshlrev_b32_e32 v54, 2, v193
	v_lshlrev_b32_e32 v55, 2, v194
	global_load_dwordx4 v[180:183], v27, s[4:5]
	global_load_dwordx4 v[166:169], v27, s[4:5] offset:512
	global_load_dwordx4 v[196:199], v170, s[80:81]
	global_load_dwordx4 v[200:203], v170, s[80:81] offset:512
	global_load_dwordx4 v[204:207], v171, s[80:81]
	global_load_dwordx4 v[208:211], v171, s[80:81] offset:512
	v_add_u32_e32 v170, 0x10000, v170
	v_add_u32_e32 v171, 0x10000, v171
	global_load_dwordx4 v[212:215], v170, s[80:81]
	global_load_dwordx4 v[216:219], v170, s[80:81] offset:512
	global_load_dwordx4 v[220:223], v171, s[80:81]
	global_load_dwordx4 v[224:227], v171, s[80:81] offset:512
	v_add_u32_e32 v170, 0x10000, v170
	v_add_u32_e32 v171, 0x10000, v171
	global_load_dwordx4 v[228:231], v170, s[80:81]
	global_load_dwordx4 v[232:235], v170, s[80:81] offset:512
	global_load_dwordx4 v[236:239], v171, s[80:81]
	global_load_dwordx4 v[240:243], v171, s[80:81] offset:512
	v_add_u32_e32 v170, 0x10000, v170
	v_add_u32_e32 v171, 0x10000, v171
	v_mov_b32_dpp v25, v140 row_ror:8 row_mask:0xf bank_mask:0xf
	v_mov_b32_dpp v26, v141 row_ror:8 row_mask:0xf bank_mask:0xf
	v_mov_b32_dpp v140, v136 row_ror:8 row_mask:0xf bank_mask:0xc
	v_mov_b32_dpp v141, v137 row_ror:8 row_mask:0xf bank_mask:0xc
	v_mov_b32_dpp v136, v25 quad_perm:[0,1,2,3] row_mask:0xf bank_mask:0x3
	v_mov_b32_dpp v137, v26 quad_perm:[0,1,2,3] row_mask:0xf bank_mask:0x3
	v_mov_b32_dpp v25, v142 row_ror:8 row_mask:0xf bank_mask:0xf
	v_mov_b32_dpp v26, v143 row_ror:8 row_mask:0xf bank_mask:0xf
	v_mov_b32_dpp v142, v138 row_ror:8 row_mask:0xf bank_mask:0xc
	v_mov_b32_dpp v143, v139 row_ror:8 row_mask:0xf bank_mask:0xc
	v_mov_b32_dpp v138, v25 quad_perm:[0,1,2,3] row_mask:0xf bank_mask:0x3
	v_mov_b32_dpp v139, v26 quad_perm:[0,1,2,3] row_mask:0xf bank_mask:0x3
	v_mov_b32_dpp v25, v132 row_ror:8 row_mask:0xf bank_mask:0xf
	v_mov_b32_dpp v26, v133 row_ror:8 row_mask:0xf bank_mask:0xf
	v_mov_b32_dpp v132, v128 row_ror:8 row_mask:0xf bank_mask:0xc
	v_mov_b32_dpp v133, v129 row_ror:8 row_mask:0xf bank_mask:0xc
	v_mov_b32_dpp v128, v25 quad_perm:[0,1,2,3] row_mask:0xf bank_mask:0x3
	v_mov_b32_dpp v129, v26 quad_perm:[0,1,2,3] row_mask:0xf bank_mask:0x3
	v_mov_b32_dpp v25, v134 row_ror:8 row_mask:0xf bank_mask:0xf
	v_mov_b32_dpp v26, v135 row_ror:8 row_mask:0xf bank_mask:0xf
	v_mov_b32_dpp v134, v130 row_ror:8 row_mask:0xf bank_mask:0xc
	v_mov_b32_dpp v135, v131 row_ror:8 row_mask:0xf bank_mask:0xc
	v_mov_b32_dpp v130, v25 quad_perm:[0,1,2,3] row_mask:0xf bank_mask:0x3
	v_mov_b32_dpp v131, v26 quad_perm:[0,1,2,3] row_mask:0xf bank_mask:0x3
	v_mov_b32_dpp v25, v124 row_ror:8 row_mask:0xf bank_mask:0xf
	v_mov_b32_dpp v26, v125 row_ror:8 row_mask:0xf bank_mask:0xf
	v_mov_b32_dpp v124, v120 row_ror:8 row_mask:0xf bank_mask:0xc
	v_mov_b32_dpp v125, v121 row_ror:8 row_mask:0xf bank_mask:0xc
	v_mov_b32_dpp v120, v25 quad_perm:[0,1,2,3] row_mask:0xf bank_mask:0x3
	v_mov_b32_dpp v121, v26 quad_perm:[0,1,2,3] row_mask:0xf bank_mask:0x3
	v_mov_b32_dpp v25, v126 row_ror:8 row_mask:0xf bank_mask:0xf
	v_mov_b32_dpp v26, v127 row_ror:8 row_mask:0xf bank_mask:0xf
	v_mov_b32_dpp v126, v122 row_ror:8 row_mask:0xf bank_mask:0xc
	v_mov_b32_dpp v127, v123 row_ror:8 row_mask:0xf bank_mask:0xc
	v_mov_b32_dpp v122, v25 quad_perm:[0,1,2,3] row_mask:0xf bank_mask:0x3
	v_mov_b32_dpp v123, v26 quad_perm:[0,1,2,3] row_mask:0xf bank_mask:0x3
	v_mov_b32_dpp v25, v116 row_ror:8 row_mask:0xf bank_mask:0xf
	v_mov_b32_dpp v26, v117 row_ror:8 row_mask:0xf bank_mask:0xf
	v_mov_b32_dpp v116, v112 row_ror:8 row_mask:0xf bank_mask:0xc
	v_mov_b32_dpp v117, v113 row_ror:8 row_mask:0xf bank_mask:0xc
	v_mov_b32_dpp v112, v25 quad_perm:[0,1,2,3] row_mask:0xf bank_mask:0x3
	v_mov_b32_dpp v113, v26 quad_perm:[0,1,2,3] row_mask:0xf bank_mask:0x3
	v_mov_b32_dpp v25, v118 row_ror:8 row_mask:0xf bank_mask:0xf
	v_mov_b32_dpp v26, v119 row_ror:8 row_mask:0xf bank_mask:0xf
	v_mov_b32_dpp v118, v114 row_ror:8 row_mask:0xf bank_mask:0xc
	v_mov_b32_dpp v119, v115 row_ror:8 row_mask:0xf bank_mask:0xc
	v_mov_b32_dpp v114, v25 quad_perm:[0,1,2,3] row_mask:0xf bank_mask:0x3
	v_mov_b32_dpp v115, v26 quad_perm:[0,1,2,3] row_mask:0xf bank_mask:0x3
	v_mov_b32_dpp v25, v108 row_ror:8 row_mask:0xf bank_mask:0xf
	v_mov_b32_dpp v26, v109 row_ror:8 row_mask:0xf bank_mask:0xf
	v_mov_b32_dpp v108, v104 row_ror:8 row_mask:0xf bank_mask:0xc
	v_mov_b32_dpp v109, v105 row_ror:8 row_mask:0xf bank_mask:0xc
	v_mov_b32_dpp v104, v25 quad_perm:[0,1,2,3] row_mask:0xf bank_mask:0x3
	v_mov_b32_dpp v105, v26 quad_perm:[0,1,2,3] row_mask:0xf bank_mask:0x3
;     __device__ __forceinline__ void operator()(const f32x4 (&acc)[2][2][4][2], const Unit& u, int wr, int wc, int fr, int fq, LAS unsigned char* lds) const {
;     ...
;             for (int m = 0; m < 4; ++m) { const size_t ro = (size_t)(row0 + ai * HALF + m * 16) * ldc + col0; float ssq = 0.f;
; #pragma unroll
;                 for (int bj = 0; bj < 2; ++bj) { const size_t o = ro + bj * HALF;
;                     const f32x4 r0 = *(const f32x4*)(res + o), r1 = *(const f32x4*)(res + o + 4);
;                     const f32x4 x0 = r0 + acc[ai][bj][m][0], x1 = r1 + acc[ai][bj][m][1];
	v_mov_b32_dpp v25, v110 row_ror:8 row_mask:0xf bank_mask:0xf
	v_mov_b32_dpp v26, v111 row_ror:8 row_mask:0xf bank_mask:0xf
	v_mov_b32_dpp v110, v106 row_ror:8 row_mask:0xf bank_mask:0xc
	v_mov_b32_dpp v111, v107 row_ror:8 row_mask:0xf bank_mask:0xc
	v_mov_b32_dpp v106, v25 quad_perm:[0,1,2,3] row_mask:0xf bank_mask:0x3
	v_mov_b32_dpp v107, v26 quad_perm:[0,1,2,3] row_mask:0xf bank_mask:0x3
	v_mov_b32_dpp v25, v100 row_ror:8 row_mask:0xf bank_mask:0xf
	v_mov_b32_dpp v26, v101 row_ror:8 row_mask:0xf bank_mask:0xf
	v_mov_b32_dpp v100, v96 row_ror:8 row_mask:0xf bank_mask:0xc
	v_mov_b32_dpp v101, v97 row_ror:8 row_mask:0xf bank_mask:0xc
	v_mov_b32_dpp v96, v25 quad_perm:[0,1,2,3] row_mask:0xf bank_mask:0x3
	v_mov_b32_dpp v97, v26 quad_perm:[0,1,2,3] row_mask:0xf bank_mask:0x3
	v_mov_b32_dpp v25, v102 row_ror:8 row_mask:0xf bank_mask:0xf
	v_mov_b32_dpp v26, v103 row_ror:8 row_mask:0xf bank_mask:0xf
	v_mov_b32_dpp v102, v98 row_ror:8 row_mask:0xf bank_mask:0xc
	v_mov_b32_dpp v103, v99 row_ror:8 row_mask:0xf bank_mask:0xc
	v_mov_b32_dpp v98, v25 quad_perm:[0,1,2,3] row_mask:0xf bank_mask:0x3
	v_mov_b32_dpp v99, v26 quad_perm:[0,1,2,3] row_mask:0xf bank_mask:0x3
	v_mov_b32_dpp v25, v92 row_ror:8 row_mask:0xf bank_mask:0xf
	v_mov_b32_dpp v26, v93 row_ror:8 row_mask:0xf bank_mask:0xf
	v_mov_b32_dpp v92, v88 row_ror:8 row_mask:0xf bank_mask:0xc
	v_mov_b32_dpp v93, v89 row_ror:8 row_mask:0xf bank_mask:0xc
	v_mov_b32_dpp v88, v25 quad_perm:[0,1,2,3] row_mask:0xf bank_mask:0x3
	v_mov_b32_dpp v89, v26 quad_perm:[0,1,2,3] row_mask:0xf bank_mask:0x3
	v_mov_b32_dpp v25, v94 row_ror:8 row_mask:0xf bank_mask:0xf
	v_mov_b32_dpp v26, v95 row_ror:8 row_mask:0xf bank_mask:0xf
	v_mov_b32_dpp v94, v90 row_ror:8 row_mask:0xf bank_mask:0xc
	v_mov_b32_dpp v95, v91 row_ror:8 row_mask:0xf bank_mask:0xc
	v_mov_b32_dpp v90, v25 quad_perm:[0,1,2,3] row_mask:0xf bank_mask:0x3
	v_mov_b32_dpp v91, v26 quad_perm:[0,1,2,3] row_mask:0xf bank_mask:0x3
	v_mov_b32_dpp v25, v84 row_ror:8 row_mask:0xf bank_mask:0xf
	v_mov_b32_dpp v26, v85 row_ror:8 row_mask:0xf bank_mask:0xf
	v_mov_b32_dpp v84, v80 row_ror:8 row_mask:0xf bank_mask:0xc
	v_mov_b32_dpp v85, v81 row_ror:8 row_mask:0xf bank_mask:0xc
	v_mov_b32_dpp v80, v25 quad_perm:[0,1,2,3] row_mask:0xf bank_mask:0x3
	v_mov_b32_dpp v81, v26 quad_perm:[0,1,2,3] row_mask:0xf bank_mask:0x3
	v_mov_b32_dpp v25, v86 row_ror:8 row_mask:0xf bank_mask:0xf
	v_mov_b32_dpp v26, v87 row_ror:8 row_mask:0xf bank_mask:0xf
	v_mov_b32_dpp v86, v82 row_ror:8 row_mask:0xf bank_mask:0xc
	v_mov_b32_dpp v87, v83 row_ror:8 row_mask:0xf bank_mask:0xc
	v_mov_b32_dpp v82, v25 quad_perm:[0,1,2,3] row_mask:0xf bank_mask:0x3
	v_mov_b32_dpp v83, v26 quad_perm:[0,1,2,3] row_mask:0xf bank_mask:0x3
	v_mov_b32_dpp v25, v76 row_ror:8 row_mask:0xf bank_mask:0xf
	v_mov_b32_dpp v26, v77 row_ror:8 row_mask:0xf bank_mask:0xf
	v_mov_b32_dpp v76, v72 row_ror:8 row_mask:0xf bank_mask:0xc
	v_mov_b32_dpp v77, v73 row_ror:8 row_mask:0xf bank_mask:0xc
	v_mov_b32_dpp v72, v25 quad_perm:[0,1,2,3] row_mask:0xf bank_mask:0x3
	v_mov_b32_dpp v73, v26 quad_perm:[0,1,2,3] row_mask:0xf bank_mask:0x3
	v_mov_b32_dpp v25, v78 row_ror:8 row_mask:0xf bank_mask:0xf
	v_mov_b32_dpp v26, v79 row_ror:8 row_mask:0xf bank_mask:0xf
	v_mov_b32_dpp v78, v74 row_ror:8 row_mask:0xf bank_mask:0xc
	v_mov_b32_dpp v79, v75 row_ror:8 row_mask:0xf bank_mask:0xc
	v_mov_b32_dpp v74, v25 quad_perm:[0,1,2,3] row_mask:0xf bank_mask:0x3
	v_mov_b32_dpp v75, v26 quad_perm:[0,1,2,3] row_mask:0xf bank_mask:0x3
	v_mov_b32_dpp v25, v68 row_ror:8 row_mask:0xf bank_mask:0xf
	v_mov_b32_dpp v26, v69 row_ror:8 row_mask:0xf bank_mask:0xf
	v_mov_b32_dpp v68, v64 row_ror:8 row_mask:0xf bank_mask:0xc
	v_mov_b32_dpp v69, v65 row_ror:8 row_mask:0xf bank_mask:0xc
	v_mov_b32_dpp v64, v25 quad_perm:[0,1,2,3] row_mask:0xf bank_mask:0x3
	v_mov_b32_dpp v65, v26 quad_perm:[0,1,2,3] row_mask:0xf bank_mask:0x3
	v_mov_b32_dpp v25, v70 row_ror:8 row_mask:0xf bank_mask:0xf
	v_mov_b32_dpp v26, v71 row_ror:8 row_mask:0xf bank_mask:0xf
	v_mov_b32_dpp v70, v66 row_ror:8 row_mask:0xf bank_mask:0xc
	v_mov_b32_dpp v71, v67 row_ror:8 row_mask:0xf bank_mask:0xc
	v_mov_b32_dpp v66, v25 quad_perm:[0,1,2,3] row_mask:0xf bank_mask:0x3
	v_mov_b32_dpp v67, v26 quad_perm:[0,1,2,3] row_mask:0xf bank_mask:0x3
	v_mov_b32_dpp v25, v60 row_ror:8 row_mask:0xf bank_mask:0xf
	v_mov_b32_dpp v26, v61 row_ror:8 row_mask:0xf bank_mask:0xf
	v_mov_b32_dpp v60, v56 row_ror:8 row_mask:0xf bank_mask:0xc
	v_mov_b32_dpp v61, v57 row_ror:8 row_mask:0xf bank_mask:0xc
	v_mov_b32_dpp v56, v25 quad_perm:[0,1,2,3] row_mask:0xf bank_mask:0x3
	v_mov_b32_dpp v57, v26 quad_perm:[0,1,2,3] row_mask:0xf bank_mask:0x3
	v_mov_b32_dpp v25, v62 row_ror:8 row_mask:0xf bank_mask:0xf
	v_mov_b32_dpp v26, v63 row_ror:8 row_mask:0xf bank_mask:0xf
	v_mov_b32_dpp v62, v58 row_ror:8 row_mask:0xf bank_mask:0xc
	v_mov_b32_dpp v63, v59 row_ror:8 row_mask:0xf bank_mask:0xc
	v_mov_b32_dpp v58, v25 quad_perm:[0,1,2,3] row_mask:0xf bank_mask:0x3
	v_mov_b32_dpp v59, v26 quad_perm:[0,1,2,3] row_mask:0xf bank_mask:0x3
	v_mov_b32_dpp v25, v44 row_ror:8 row_mask:0xf bank_mask:0xf
	v_mov_b32_dpp v26, v45 row_ror:8 row_mask:0xf bank_mask:0xf
	v_mov_b32_dpp v44, v40 row_ror:8 row_mask:0xf bank_mask:0xc
	v_mov_b32_dpp v45, v41 row_ror:8 row_mask:0xf bank_mask:0xc
	v_mov_b32_dpp v40, v25 quad_perm:[0,1,2,3] row_mask:0xf bank_mask:0x3
	v_mov_b32_dpp v41, v26 quad_perm:[0,1,2,3] row_mask:0xf bank_mask:0x3
	v_mov_b32_dpp v25, v46 row_ror:8 row_mask:0xf bank_mask:0xf
	v_mov_b32_dpp v26, v47 row_ror:8 row_mask:0xf bank_mask:0xf
	v_mov_b32_dpp v46, v42 row_ror:8 row_mask:0xf bank_mask:0xc
	v_mov_b32_dpp v47, v43 row_ror:8 row_mask:0xf bank_mask:0xc
; __device__ __forceinline__ unsigned cvt_pk_bf16(float lo, float hi) { unsigned r; asm volatile("v_cvt_pk_bf16_f32 %0, %1, %2" : "=v"(r) : "v"(lo), "v"(hi)); return r; }
;     __device__ __forceinline__ void operator()(const f32x4 (&acc)[2][2][4][2], const Unit& u, int wr, int wc, int fr, int fq, LAS unsigned char* lds) const {
;     ...
;             for (int m = 0; m < 4; ++m) { const size_t ro = (size_t)(row0 + ai * HALF + m * 16) * ldc + col0; float ssq = 0.f;
; #pragma unroll
;                 for (int bj = 0; bj < 2; ++bj) { const size_t o = ro + bj * HALF;
;                     const f32x4 r0 = *(const f32x4*)(res + o), r1 = *(const f32x4*)(res + o + 4);
;                     const f32x4 x0 = r0 + acc[ai][bj][m][0], x1 = r1 + acc[ai][bj][m][1];
;                     *(f32x4*)(O + o) = x0; *(f32x4*)(O + o + 4) = x1;
;                     u32x4 hb; hb.x = cvt_pk_bf16(x0[0] * gg[bj][0][0], x0[1] * gg[bj][0][1]); hb.y = cvt_pk_bf16(x0[2] * gg[bj][0][2], x0[3] * gg[bj][0][3]);
;                     hb.z = cvt_pk_bf16(x1[0] * gg[bj][1][0], x1[1] * gg[bj][1][1]); hb.w = cvt_pk_bf16(x1[2] * gg[bj][1][2], x1[3] * gg[bj][1][3]);
;                     *(u32x4*)(H + o) = hb;
;                     ssq += ((x0[0] * x0[0] + x0[1] * x0[1]) + (x0[2] * x0[2] + x0[3] * x0[3])) + ((x1[0] * x1[0] + x1[1] * x1[1]) + (x1[2] * x1[2] + x1[3] * x1[3])); }
;                 ssq += __shfl_xor(ssq, 16); ssq += __shfl_xor(ssq, 32);
	v_mov_b32_dpp v42, v25 quad_perm:[0,1,2,3] row_mask:0xf bank_mask:0x3
	v_mov_b32_dpp v43, v26 quad_perm:[0,1,2,3] row_mask:0xf bank_mask:0x3
	v_mov_b32_dpp v25, v36 row_ror:8 row_mask:0xf bank_mask:0xf
	v_mov_b32_dpp v26, v37 row_ror:8 row_mask:0xf bank_mask:0xf
	v_mov_b32_dpp v36, v32 row_ror:8 row_mask:0xf bank_mask:0xc
	v_mov_b32_dpp v37, v33 row_ror:8 row_mask:0xf bank_mask:0xc
	v_mov_b32_dpp v32, v25 quad_perm:[0,1,2,3] row_mask:0xf bank_mask:0x3
	v_mov_b32_dpp v33, v26 quad_perm:[0,1,2,3] row_mask:0xf bank_mask:0x3
	v_mov_b32_dpp v25, v38 row_ror:8 row_mask:0xf bank_mask:0xf
	v_mov_b32_dpp v26, v39 row_ror:8 row_mask:0xf bank_mask:0xf
	v_mov_b32_dpp v38, v34 row_ror:8 row_mask:0xf bank_mask:0xc
	v_mov_b32_dpp v39, v35 row_ror:8 row_mask:0xf bank_mask:0xc
	v_mov_b32_dpp v34, v25 quad_perm:[0,1,2,3] row_mask:0xf bank_mask:0x3
	v_mov_b32_dpp v35, v26 quad_perm:[0,1,2,3] row_mask:0xf bank_mask:0x3
	v_mov_b32_dpp v25, v20 row_ror:8 row_mask:0xf bank_mask:0xf
	v_mov_b32_dpp v26, v21 row_ror:8 row_mask:0xf bank_mask:0xf
	v_mov_b32_dpp v20, v16 row_ror:8 row_mask:0xf bank_mask:0xc
	v_mov_b32_dpp v21, v17 row_ror:8 row_mask:0xf bank_mask:0xc
	v_mov_b32_dpp v16, v25 quad_perm:[0,1,2,3] row_mask:0xf bank_mask:0x3
	v_mov_b32_dpp v17, v26 quad_perm:[0,1,2,3] row_mask:0xf bank_mask:0x3
	v_mov_b32_dpp v25, v22 row_ror:8 row_mask:0xf bank_mask:0xf
	v_mov_b32_dpp v26, v23 row_ror:8 row_mask:0xf bank_mask:0xf
	v_mov_b32_dpp v22, v18 row_ror:8 row_mask:0xf bank_mask:0xc
	v_mov_b32_dpp v23, v19 row_ror:8 row_mask:0xf bank_mask:0xc
	v_mov_b32_dpp v18, v25 quad_perm:[0,1,2,3] row_mask:0xf bank_mask:0x3
	v_mov_b32_dpp v19, v26 quad_perm:[0,1,2,3] row_mask:0xf bank_mask:0x3
	v_mov_b32_dpp v25, v12 row_ror:8 row_mask:0xf bank_mask:0xf
	v_mov_b32_dpp v26, v13 row_ror:8 row_mask:0xf bank_mask:0xf
	v_mov_b32_dpp v12, v8 row_ror:8 row_mask:0xf bank_mask:0xc
	v_mov_b32_dpp v13, v9 row_ror:8 row_mask:0xf bank_mask:0xc
	v_mov_b32_dpp v8, v25 quad_perm:[0,1,2,3] row_mask:0xf bank_mask:0x3
	v_mov_b32_dpp v9, v26 quad_perm:[0,1,2,3] row_mask:0xf bank_mask:0x3
	v_mov_b32_dpp v25, v14 row_ror:8 row_mask:0xf bank_mask:0xf
	v_mov_b32_dpp v26, v15 row_ror:8 row_mask:0xf bank_mask:0xf
	v_mov_b32_dpp v14, v10 row_ror:8 row_mask:0xf bank_mask:0xc
	v_mov_b32_dpp v15, v11 row_ror:8 row_mask:0xf bank_mask:0xc
	v_mov_b32_dpp v10, v25 quad_perm:[0,1,2,3] row_mask:0xf bank_mask:0x3
	v_mov_b32_dpp v11, v26 quad_perm:[0,1,2,3] row_mask:0xf bank_mask:0x3
	v_mov_b32_dpp v25, v4 row_ror:8 row_mask:0xf bank_mask:0xf
	v_mov_b32_dpp v26, v5 row_ror:8 row_mask:0xf bank_mask:0xf
	v_mov_b32_dpp v4, v0 row_ror:8 row_mask:0xf bank_mask:0xc
	v_mov_b32_dpp v5, v1 row_ror:8 row_mask:0xf bank_mask:0xc
	v_mov_b32_dpp v0, v25 quad_perm:[0,1,2,3] row_mask:0xf bank_mask:0x3
	v_mov_b32_dpp v1, v26 quad_perm:[0,1,2,3] row_mask:0xf bank_mask:0x3
	v_mov_b32_dpp v25, v6 row_ror:8 row_mask:0xf bank_mask:0xf
	v_mov_b32_dpp v26, v7 row_ror:8 row_mask:0xf bank_mask:0xf
	v_mov_b32_dpp v6, v2 row_ror:8 row_mask:0xf bank_mask:0xc
	v_mov_b32_dpp v7, v3 row_ror:8 row_mask:0xf bank_mask:0xc
	v_mov_b32_dpp v2, v25 quad_perm:[0,1,2,3] row_mask:0xf bank_mask:0x3
	v_mov_b32_dpp v3, v26 quad_perm:[0,1,2,3] row_mask:0xf bank_mask:0x3
	s_waitcnt vmcnt(8)
	v_pk_add_f32 v[140:141], v[140:141], v[196:197]
	v_pk_add_f32 v[142:143], v[142:143], v[198:199]
	v_pk_add_f32 v[132:133], v[132:133], v[200:201]
	v_pk_add_f32 v[134:135], v[134:135], v[202:203]
	v_pk_add_f32 v[136:137], v[136:137], v[204:205]
	v_pk_add_f32 v[138:139], v[138:139], v[206:207]
	v_pk_add_f32 v[128:129], v[128:129], v[208:209]
	v_pk_add_f32 v[130:131], v[130:131], v[210:211]
	global_store_dwordx4 v177, v[140:143], s[76:77]
	global_store_dwordx4 v177, v[132:135], s[76:77] offset:512
	global_store_dwordx4 v195, v[136:139], s[76:77]
	global_store_dwordx4 v195, v[128:131], s[76:77] offset:512
	global_load_dwordx4 v[196:199], v170, s[80:81]
	global_load_dwordx4 v[200:203], v170, s[80:81] offset:512
	global_load_dwordx4 v[204:207], v171, s[80:81]
	global_load_dwordx4 v[208:211], v171, s[80:81] offset:512
	v_add_u32_e32 v170, 0x50000, v170
	v_add_u32_e32 v171, 0x50000, v171
	v_mul_f32_e32 v27, v180, v140
	v_mul_f32_e32 v28, v181, v141
	v_cvt_pk_bf16_f32 v30, v27, v28
	v_mul_f32_e32 v27, v182, v142
	v_mul_f32_e32 v28, v183, v143
	v_cvt_pk_bf16_f32 v31, v27, v28
	global_store_dwordx2 v247, v[30:31], s[88:89]
	v_mul_f32_e32 v27, v166, v132
	v_mul_f32_e32 v28, v167, v133
	v_cvt_pk_bf16_f32 v48, v27, v28
	v_mul_f32_e32 v27, v168, v134
	v_mul_f32_e32 v28, v169, v135
	v_cvt_pk_bf16_f32 v49, v27, v28
	global_store_dwordx2 v247, v[48:49], s[88:89] offset:256
	v_mul_f32_e32 v27, v180, v136
	v_mul_f32_e32 v28, v181, v137
	v_cvt_pk_bf16_f32 v30, v27, v28
	v_mul_f32_e32 v27, v182, v138
	v_mul_f32_e32 v28, v183, v139
	v_cvt_pk_bf16_f32 v31, v27, v28
	global_store_dwordx2 v24, v[30:31], s[88:89]
	v_mul_f32_e32 v27, v166, v128
	v_mul_f32_e32 v28, v167, v129
	v_cvt_pk_bf16_f32 v48, v27, v28
	v_mul_f32_e32 v27, v168, v130
	v_mul_f32_e32 v28, v169, v131
	v_cvt_pk_bf16_f32 v49, v27, v28
	global_store_dwordx2 v24, v[48:49], s[88:89] offset:256
	v_mul_f32_e32 v50, v141, v141
	v_mul_f32_e32 v29, v143, v143
	v_fmac_f32_e32 v50, v140, v140
	v_fmac_f32_e32 v29, v142, v142
	v_add_f32_e32 v50, v50, v29
	v_mul_f32_e32 v51, v137, v137
	v_mul_f32_e32 v29, v139, v139
	v_fmac_f32_e32 v51, v136, v136
	v_fmac_f32_e32 v29, v138, v138
	v_add_f32_e32 v51, v51, v29
	v_mul_f32_e32 v52, v133, v133
	v_mul_f32_e32 v29, v135, v135
	v_fmac_f32_e32 v52, v132, v132
	v_fmac_f32_e32 v29, v134, v134
	v_add_f32_e32 v52, v52, v29
	v_mul_f32_e32 v53, v129, v129
	v_mul_f32_e32 v29, v131, v131
	v_fmac_f32_e32 v53, v128, v128
	v_fmac_f32_e32 v29, v130, v130
	v_add_f32_e32 v53, v53, v29
	v_add_f32_dpp v27, v50, v50 row_ror:8 row_mask:0xf bank_mask:0x3
	v_add_f32_dpp v28, v52, v52 row_ror:8 row_mask:0xf bank_mask:0x3
	v_add_f32_dpp v27, v51, v51 row_ror:8 row_mask:0xf bank_mask:0xc
	v_add_f32_dpp v28, v53, v53 row_ror:8 row_mask:0xf bank_mask:0xc
	v_add_f32_e32 v27, v27, v28
	ds_bpermute_b32 v29, v54, v27
	s_waitcnt lgkmcnt(0)
; __device__ __forceinline__ unsigned cvt_pk_bf16(float lo, float hi) { unsigned r; asm volatile("v_cvt_pk_bf16_f32 %0, %1, %2" : "=v"(r) : "v"(lo), "v"(hi)); return r; }
;     __device__ __forceinline__ void operator()(const f32x4 (&acc)[2][2][4][2], const Unit& u, int wr, int wc, int fr, int fq, LAS unsigned char* lds) const {
;     ...
;             for (int m = 0; m < 4; ++m) { const size_t ro = (size_t)(row0 + ai * HALF + m * 16) * ldc + col0; float ssq = 0.f;
; #pragma unroll
;                 for (int bj = 0; bj < 2; ++bj) { const size_t o = ro + bj * HALF;
;                     const f32x4 r0 = *(const f32x4*)(res + o), r1 = *(const f32x4*)(res + o + 4);
;                     const f32x4 x0 = r0 + acc[ai][bj][m][0], x1 = r1 + acc[ai][bj][m][1];
;                     *(f32x4*)(O + o) = x0; *(f32x4*)(O + o + 4) = x1;
;                     u32x4 hb; hb.x = cvt_pk_bf16(x0[0] * gg[bj][0][0], x0[1] * gg[bj][0][1]); hb.y = cvt_pk_bf16(x0[2] * gg[bj][0][2], x0[3] * gg[bj][0][3]);
;                     hb.z = cvt_pk_bf16(x1[0] * gg[bj][1][0], x1[1] * gg[bj][1][1]); hb.w = cvt_pk_bf16(x1[2] * gg[bj][1][2], x1[3] * gg[bj][1][3]);
;                     *(u32x4*)(H + o) = hb;
;                     ssq += ((x0[0] * x0[0] + x0[1] * x0[1]) + (x0[2] * x0[2] + x0[3] * x0[3])) + ((x1[0] * x1[0] + x1[1] * x1[1]) + (x1[2] * x1[2] + x1[3] * x1[3])); }
;                 ssq += __shfl_xor(ssq, 16); ssq += __shfl_xor(ssq, 32);
;                 if (fq == 0) part[(ai * HALF + wr * 64 + m * 16 + fr) * 4 + wc] = ssq; }
	v_add_f32_e32 v27, v27, v29
	ds_bpermute_b32 v29, v55, v27
	s_waitcnt lgkmcnt(0)
	v_add_f32_e32 v27, v27, v29
	s_and_saveexec_b64 s[14:15], s[42:43]
	ds_write_b32 v176, v27
	s_or_b64 exec, exec, s[14:15]
	v_add_u32_e32 v177, 0x10000, v177
	v_add_u32_e32 v195, 0x10000, v195
	v_add_u32_e32 v247, 0x8000, v247
	v_add_u32_e32 v24, 0x8000, v24
	s_waitcnt vmcnt(16)
	v_pk_add_f32 v[124:125], v[124:125], v[212:213]
	v_pk_add_f32 v[126:127], v[126:127], v[214:215]
	v_pk_add_f32 v[116:117], v[116:117], v[216:217]
	v_pk_add_f32 v[118:119], v[118:119], v[218:219]
	v_pk_add_f32 v[120:121], v[120:121], v[220:221]
	v_pk_add_f32 v[122:123], v[122:123], v[222:223]
	v_pk_add_f32 v[112:113], v[112:113], v[224:225]
	v_pk_add_f32 v[114:115], v[114:115], v[226:227]
	global_store_dwordx4 v177, v[124:127], s[76:77]
	global_store_dwordx4 v177, v[116:119], s[76:77] offset:512
	global_store_dwordx4 v195, v[120:123], s[76:77]
	global_store_dwordx4 v195, v[112:115], s[76:77] offset:512
	global_load_dwordx4 v[212:215], v170, s[80:81]
	global_load_dwordx4 v[216:219], v170, s[80:81] offset:512
	global_load_dwordx4 v[220:223], v171, s[80:81]
	global_load_dwordx4 v[224:227], v171, s[80:81] offset:512
	v_add_u32_e32 v170, 0x10000, v170
	v_add_u32_e32 v171, 0x10000, v171
	v_mul_f32_e32 v27, v180, v124
	v_mul_f32_e32 v28, v181, v125
	v_cvt_pk_bf16_f32 v30, v27, v28
	v_mul_f32_e32 v27, v182, v126
	v_mul_f32_e32 v28, v183, v127
	v_cvt_pk_bf16_f32 v31, v27, v28
	global_store_dwordx2 v247, v[30:31], s[88:89]
	v_mul_f32_e32 v27, v166, v116
	v_mul_f32_e32 v28, v167, v117
	v_cvt_pk_bf16_f32 v48, v27, v28
	v_mul_f32_e32 v27, v168, v118
	v_mul_f32_e32 v28, v169, v119
	v_cvt_pk_bf16_f32 v49, v27, v28
	global_store_dwordx2 v247, v[48:49], s[88:89] offset:256
	v_mul_f32_e32 v27, v180, v120
	v_mul_f32_e32 v28, v181, v121
	v_cvt_pk_bf16_f32 v30, v27, v28
	v_mul_f32_e32 v27, v182, v122
	v_mul_f32_e32 v28, v183, v123
	v_cvt_pk_bf16_f32 v31, v27, v28
	global_store_dwordx2 v24, v[30:31], s[88:89]
	v_mul_f32_e32 v27, v166, v112
	v_mul_f32_e32 v28, v167, v113
	v_cvt_pk_bf16_f32 v48, v27, v28
	v_mul_f32_e32 v27, v168, v114
	v_mul_f32_e32 v28, v169, v115
	v_cvt_pk_bf16_f32 v49, v27, v28
	global_store_dwordx2 v24, v[48:49], s[88:89] offset:256
	v_mul_f32_e32 v50, v125, v125
	v_mul_f32_e32 v29, v127, v127
	v_fmac_f32_e32 v50, v124, v124
	v_fmac_f32_e32 v29, v126, v126
	v_add_f32_e32 v50, v50, v29
	v_mul_f32_e32 v51, v121, v121
	v_mul_f32_e32 v29, v123, v123
	v_fmac_f32_e32 v51, v120, v120
	v_fmac_f32_e32 v29, v122, v122
	v_add_f32_e32 v51, v51, v29
	v_mul_f32_e32 v52, v117, v117
	v_mul_f32_e32 v29, v119, v119
	v_fmac_f32_e32 v52, v116, v116
	v_fmac_f32_e32 v29, v118, v118
	v_add_f32_e32 v52, v52, v29
	v_mul_f32_e32 v53, v113, v113
	v_mul_f32_e32 v29, v115, v115
	v_fmac_f32_e32 v53, v112, v112
	v_fmac_f32_e32 v29, v114, v114
	v_add_f32_e32 v53, v53, v29
	v_add_f32_dpp v27, v50, v50 row_ror:8 row_mask:0xf bank_mask:0x3
	v_add_f32_dpp v28, v52, v52 row_ror:8 row_mask:0xf bank_mask:0x3
	v_add_f32_dpp v27, v51, v51 row_ror:8 row_mask:0xf bank_mask:0xc
	v_add_f32_dpp v28, v53, v53 row_ror:8 row_mask:0xf bank_mask:0xc
	v_add_f32_e32 v27, v27, v28
	ds_bpermute_b32 v29, v54, v27
	s_waitcnt lgkmcnt(0)
	v_add_f32_e32 v27, v27, v29
	ds_bpermute_b32 v29, v55, v27
	s_waitcnt lgkmcnt(0)
	v_add_f32_e32 v27, v27, v29
	s_and_saveexec_b64 s[14:15], s[42:43]
	ds_write_b32 v176, v27 offset:256
	s_or_b64 exec, exec, s[14:15]
	v_add_u32_e32 v177, 0x10000, v177
	v_add_u32_e32 v195, 0x10000, v195
	v_add_u32_e32 v247, 0x8000, v247
	v_add_u32_e32 v24, 0x8000, v24
	s_waitcnt vmcnt(24)
	v_pk_add_f32 v[108:109], v[108:109], v[228:229]
	v_pk_add_f32 v[110:111], v[110:111], v[230:231]
	v_pk_add_f32 v[100:101], v[100:101], v[232:233]
	v_pk_add_f32 v[102:103], v[102:103], v[234:235]
	v_pk_add_f32 v[104:105], v[104:105], v[236:237]
	v_pk_add_f32 v[106:107], v[106:107], v[238:239]
	v_pk_add_f32 v[96:97], v[96:97], v[240:241]
	v_pk_add_f32 v[98:99], v[98:99], v[242:243]
	global_store_dwordx4 v177, v[108:111], s[76:77]
	global_store_dwordx4 v177, v[100:103], s[76:77] offset:512
	global_store_dwordx4 v195, v[104:107], s[76:77]
	global_store_dwordx4 v195, v[96:99], s[76:77] offset:512
	global_load_dwordx4 v[228:231], v170, s[80:81]
	global_load_dwordx4 v[232:235], v170, s[80:81] offset:512
	global_load_dwordx4 v[236:239], v171, s[80:81]
	global_load_dwordx4 v[240:243], v171, s[80:81] offset:512
	v_add_u32_e32 v170, 0x10000, v170
	v_add_u32_e32 v171, 0x10000, v171
	v_mul_f32_e32 v27, v180, v108
	v_mul_f32_e32 v28, v181, v109
	v_cvt_pk_bf16_f32 v30, v27, v28
	v_mul_f32_e32 v27, v182, v110
	v_mul_f32_e32 v28, v183, v111
	v_cvt_pk_bf16_f32 v31, v27, v28
	global_store_dwordx2 v247, v[30:31], s[88:89]
	v_mul_f32_e32 v27, v166, v100
	v_mul_f32_e32 v28, v167, v101
	v_cvt_pk_bf16_f32 v48, v27, v28
	v_mul_f32_e32 v27, v168, v102
	v_mul_f32_e32 v28, v169, v103
	v_cvt_pk_bf16_f32 v49, v27, v28
	global_store_dwordx2 v247, v[48:49], s[88:89] offset:256
	v_mul_f32_e32 v27, v180, v104
	v_mul_f32_e32 v28, v181, v105
	v_cvt_pk_bf16_f32 v30, v27, v28
	v_mul_f32_e32 v27, v182, v106
	v_mul_f32_e32 v28, v183, v107
	v_cvt_pk_bf16_f32 v31, v27, v28
	global_store_dwordx2 v24, v[30:31], s[88:89]
	v_mul_f32_e32 v27, v166, v96
	v_mul_f32_e32 v28, v167, v97
	v_cvt_pk_bf16_f32 v48, v27, v28
	v_mul_f32_e32 v27, v168, v98
	v_mul_f32_e32 v28, v169, v99
	v_cvt_pk_bf16_f32 v49, v27, v28
	global_store_dwordx2 v24, v[48:49], s[88:89] offset:256
	v_mul_f32_e32 v50, v109, v109
	v_mul_f32_e32 v29, v111, v111
	v_fmac_f32_e32 v50, v108, v108
	v_fmac_f32_e32 v29, v110, v110
	v_add_f32_e32 v50, v50, v29
	v_mul_f32_e32 v51, v105, v105
	v_mul_f32_e32 v29, v107, v107
	v_fmac_f32_e32 v51, v104, v104
	v_fmac_f32_e32 v29, v106, v106
	v_add_f32_e32 v51, v51, v29
	v_mul_f32_e32 v52, v101, v101
	v_mul_f32_e32 v29, v103, v103
	v_fmac_f32_e32 v52, v100, v100
	v_fmac_f32_e32 v29, v102, v102
	v_add_f32_e32 v52, v52, v29
	v_mul_f32_e32 v53, v97, v97
	v_mul_f32_e32 v29, v99, v99
	v_fmac_f32_e32 v53, v96, v96
	v_fmac_f32_e32 v29, v98, v98
	v_add_f32_e32 v53, v53, v29
	v_add_f32_dpp v27, v50, v50 row_ror:8 row_mask:0xf bank_mask:0x3
	v_add_f32_dpp v28, v52, v52 row_ror:8 row_mask:0xf bank_mask:0x3
	v_add_f32_dpp v27, v51, v51 row_ror:8 row_mask:0xf bank_mask:0xc
	v_add_f32_dpp v28, v53, v53 row_ror:8 row_mask:0xf bank_mask:0xc
	v_add_f32_e32 v27, v27, v28
	ds_bpermute_b32 v29, v54, v27
	s_waitcnt lgkmcnt(0)
; __device__ __forceinline__ unsigned cvt_pk_bf16(float lo, float hi) { unsigned r; asm volatile("v_cvt_pk_bf16_f32 %0, %1, %2" : "=v"(r) : "v"(lo), "v"(hi)); return r; }
;     __device__ __forceinline__ void operator()(const f32x4 (&acc)[2][2][4][2], const Unit& u, int wr, int wc, int fr, int fq, LAS unsigned char* lds) const {
;     ...
;             for (int m = 0; m < 4; ++m) { const size_t ro = (size_t)(row0 + ai * HALF + m * 16) * ldc + col0; float ssq = 0.f;
; #pragma unroll
;                 for (int bj = 0; bj < 2; ++bj) { const size_t o = ro + bj * HALF;
;                     const f32x4 r0 = *(const f32x4*)(res + o), r1 = *(const f32x4*)(res + o + 4);
;                     const f32x4 x0 = r0 + acc[ai][bj][m][0], x1 = r1 + acc[ai][bj][m][1];
;                     *(f32x4*)(O + o) = x0; *(f32x4*)(O + o + 4) = x1;
;                     u32x4 hb; hb.x = cvt_pk_bf16(x0[0] * gg[bj][0][0], x0[1] * gg[bj][0][1]); hb.y = cvt_pk_bf16(x0[2] * gg[bj][0][2], x0[3] * gg[bj][0][3]);
;                     hb.z = cvt_pk_bf16(x1[0] * gg[bj][1][0], x1[1] * gg[bj][1][1]); hb.w = cvt_pk_bf16(x1[2] * gg[bj][1][2], x1[3] * gg[bj][1][3]);
;                     *(u32x4*)(H + o) = hb;
;                     ssq += ((x0[0] * x0[0] + x0[1] * x0[1]) + (x0[2] * x0[2] + x0[3] * x0[3])) + ((x1[0] * x1[0] + x1[1] * x1[1]) + (x1[2] * x1[2] + x1[3] * x1[3])); }
;                 ssq += __shfl_xor(ssq, 16); ssq += __shfl_xor(ssq, 32);
;                 if (fq == 0) part[(ai * HALF + wr * 64 + m * 16 + fr) * 4 + wc] = ssq; }
	v_add_f32_e32 v27, v27, v29
	ds_bpermute_b32 v29, v55, v27
	s_waitcnt lgkmcnt(0)
	v_add_f32_e32 v27, v27, v29
	s_and_saveexec_b64 s[14:15], s[42:43]
	ds_write_b32 v176, v27 offset:512
	s_or_b64 exec, exec, s[14:15]
	v_add_u32_e32 v177, 0x10000, v177
	v_add_u32_e32 v195, 0x10000, v195
	v_add_u32_e32 v247, 0x8000, v247
	v_add_u32_e32 v24, 0x8000, v24
	s_waitcnt vmcnt(28)
	v_pk_add_f32 v[92:93], v[92:93], v[196:197]
	v_pk_add_f32 v[94:95], v[94:95], v[198:199]
	v_pk_add_f32 v[84:85], v[84:85], v[200:201]
	v_pk_add_f32 v[86:87], v[86:87], v[202:203]
	v_pk_add_f32 v[88:89], v[88:89], v[204:205]
	v_pk_add_f32 v[90:91], v[90:91], v[206:207]
	v_pk_add_f32 v[80:81], v[80:81], v[208:209]
	v_pk_add_f32 v[82:83], v[82:83], v[210:211]
	global_store_dwordx4 v177, v[92:95], s[76:77]
	global_store_dwordx4 v177, v[84:87], s[76:77] offset:512
	global_store_dwordx4 v195, v[88:91], s[76:77]
	global_store_dwordx4 v195, v[80:83], s[76:77] offset:512
	global_load_dwordx4 v[196:199], v170, s[80:81]
	global_load_dwordx4 v[200:203], v170, s[80:81] offset:512
	global_load_dwordx4 v[204:207], v171, s[80:81]
	global_load_dwordx4 v[208:211], v171, s[80:81] offset:512
	v_add_u32_e32 v170, 0x10000, v170
	v_add_u32_e32 v171, 0x10000, v171
	v_mul_f32_e32 v27, v180, v92
	v_mul_f32_e32 v28, v181, v93
	v_cvt_pk_bf16_f32 v30, v27, v28
	v_mul_f32_e32 v27, v182, v94
	v_mul_f32_e32 v28, v183, v95
	v_cvt_pk_bf16_f32 v31, v27, v28
	global_store_dwordx2 v247, v[30:31], s[88:89]
	v_mul_f32_e32 v27, v166, v84
	v_mul_f32_e32 v28, v167, v85
	v_cvt_pk_bf16_f32 v48, v27, v28
	v_mul_f32_e32 v27, v168, v86
	v_mul_f32_e32 v28, v169, v87
	v_cvt_pk_bf16_f32 v49, v27, v28
	global_store_dwordx2 v247, v[48:49], s[88:89] offset:256
	v_mul_f32_e32 v27, v180, v88
	v_mul_f32_e32 v28, v181, v89
	v_cvt_pk_bf16_f32 v30, v27, v28
	v_mul_f32_e32 v27, v182, v90
	v_mul_f32_e32 v28, v183, v91
	v_cvt_pk_bf16_f32 v31, v27, v28
	global_store_dwordx2 v24, v[30:31], s[88:89]
	v_mul_f32_e32 v27, v166, v80
	v_mul_f32_e32 v28, v167, v81
	v_cvt_pk_bf16_f32 v48, v27, v28
	v_mul_f32_e32 v27, v168, v82
	v_mul_f32_e32 v28, v169, v83
	v_cvt_pk_bf16_f32 v49, v27, v28
	global_store_dwordx2 v24, v[48:49], s[88:89] offset:256
	v_mul_f32_e32 v50, v93, v93
	v_mul_f32_e32 v29, v95, v95
	v_fmac_f32_e32 v50, v92, v92
	v_fmac_f32_e32 v29, v94, v94
	v_add_f32_e32 v50, v50, v29
	v_mul_f32_e32 v51, v89, v89
	v_mul_f32_e32 v29, v91, v91
	v_fmac_f32_e32 v51, v88, v88
	v_fmac_f32_e32 v29, v90, v90
	v_add_f32_e32 v51, v51, v29
	v_mul_f32_e32 v52, v85, v85
	v_mul_f32_e32 v29, v87, v87
	v_fmac_f32_e32 v52, v84, v84
	v_fmac_f32_e32 v29, v86, v86
	v_add_f32_e32 v52, v52, v29
	v_mul_f32_e32 v53, v81, v81
	v_mul_f32_e32 v29, v83, v83
	v_fmac_f32_e32 v53, v80, v80
	v_fmac_f32_e32 v29, v82, v82
	v_add_f32_e32 v53, v53, v29
	v_add_f32_dpp v27, v50, v50 row_ror:8 row_mask:0xf bank_mask:0x3
	v_add_f32_dpp v28, v52, v52 row_ror:8 row_mask:0xf bank_mask:0x3
	v_add_f32_dpp v27, v51, v51 row_ror:8 row_mask:0xf bank_mask:0xc
	v_add_f32_dpp v28, v53, v53 row_ror:8 row_mask:0xf bank_mask:0xc
	v_add_f32_e32 v27, v27, v28
	ds_bpermute_b32 v29, v54, v27
	s_waitcnt lgkmcnt(0)
	v_add_f32_e32 v27, v27, v29
	ds_bpermute_b32 v29, v55, v27
	s_waitcnt lgkmcnt(0)
	v_add_f32_e32 v27, v27, v29
	s_and_saveexec_b64 s[14:15], s[42:43]
	ds_write_b32 v176, v27 offset:768
	s_or_b64 exec, exec, s[14:15]
	v_add_u32_e32 v177, 0x50000, v177
	v_add_u32_e32 v195, 0x50000, v195
	v_add_u32_e32 v247, 0x28000, v247
	v_add_u32_e32 v24, 0x28000, v24
	s_waitcnt vmcnt(28)
	v_pk_add_f32 v[76:77], v[76:77], v[212:213]
	v_pk_add_f32 v[78:79], v[78:79], v[214:215]
	v_pk_add_f32 v[68:69], v[68:69], v[216:217]
	v_pk_add_f32 v[70:71], v[70:71], v[218:219]
	v_pk_add_f32 v[72:73], v[72:73], v[220:221]
	v_pk_add_f32 v[74:75], v[74:75], v[222:223]
	v_pk_add_f32 v[64:65], v[64:65], v[224:225]
	v_pk_add_f32 v[66:67], v[66:67], v[226:227]
	global_store_dwordx4 v177, v[76:79], s[76:77]
	global_store_dwordx4 v177, v[68:71], s[76:77] offset:512
	global_store_dwordx4 v195, v[72:75], s[76:77]
	global_store_dwordx4 v195, v[64:67], s[76:77] offset:512
	global_load_dwordx4 v[212:215], v170, s[80:81]
	global_load_dwordx4 v[216:219], v170, s[80:81] offset:512
	global_load_dwordx4 v[220:223], v171, s[80:81]
	global_load_dwordx4 v[224:227], v171, s[80:81] offset:512
	v_mul_f32_e32 v27, v180, v76
	v_mul_f32_e32 v28, v181, v77
	v_cvt_pk_bf16_f32 v30, v27, v28
	v_mul_f32_e32 v27, v182, v78
	v_mul_f32_e32 v28, v183, v79
	v_cvt_pk_bf16_f32 v31, v27, v28
	global_store_dwordx2 v247, v[30:31], s[88:89]
	v_mul_f32_e32 v27, v166, v68
	v_mul_f32_e32 v28, v167, v69
	v_cvt_pk_bf16_f32 v48, v27, v28
	v_mul_f32_e32 v27, v168, v70
	v_mul_f32_e32 v28, v169, v71
	v_cvt_pk_bf16_f32 v49, v27, v28
	global_store_dwordx2 v247, v[48:49], s[88:89] offset:256
	v_mul_f32_e32 v27, v180, v72
	v_mul_f32_e32 v28, v181, v73
	v_cvt_pk_bf16_f32 v30, v27, v28
	v_mul_f32_e32 v27, v182, v74
	v_mul_f32_e32 v28, v183, v75
	v_cvt_pk_bf16_f32 v31, v27, v28
	global_store_dwordx2 v24, v[30:31], s[88:89]
	v_mul_f32_e32 v27, v166, v64
	v_mul_f32_e32 v28, v167, v65
	v_cvt_pk_bf16_f32 v48, v27, v28
	v_mul_f32_e32 v27, v168, v66
	v_mul_f32_e32 v28, v169, v67
	v_cvt_pk_bf16_f32 v49, v27, v28
	global_store_dwordx2 v24, v[48:49], s[88:89] offset:256
	v_mul_f32_e32 v50, v77, v77
	v_mul_f32_e32 v29, v79, v79
	v_fmac_f32_e32 v50, v76, v76
	v_fmac_f32_e32 v29, v78, v78
	v_add_f32_e32 v50, v50, v29
	v_mul_f32_e32 v51, v73, v73
	v_mul_f32_e32 v29, v75, v75
	v_fmac_f32_e32 v51, v72, v72
	v_fmac_f32_e32 v29, v74, v74
	v_add_f32_e32 v51, v51, v29
	v_mul_f32_e32 v52, v69, v69
	v_mul_f32_e32 v29, v71, v71
	v_fmac_f32_e32 v52, v68, v68
	v_fmac_f32_e32 v29, v70, v70
	v_add_f32_e32 v52, v52, v29
	v_mul_f32_e32 v53, v65, v65
	v_mul_f32_e32 v29, v67, v67
	v_fmac_f32_e32 v53, v64, v64
	v_fmac_f32_e32 v29, v66, v66
	v_add_f32_e32 v53, v53, v29
	v_add_f32_dpp v27, v50, v50 row_ror:8 row_mask:0xf bank_mask:0x3
	v_add_f32_dpp v28, v52, v52 row_ror:8 row_mask:0xf bank_mask:0x3
	v_add_f32_dpp v27, v51, v51 row_ror:8 row_mask:0xf bank_mask:0xc
	v_add_f32_dpp v28, v53, v53 row_ror:8 row_mask:0xf bank_mask:0xc
	v_add_f32_e32 v27, v27, v28
	ds_bpermute_b32 v29, v54, v27
	s_waitcnt lgkmcnt(0)
; __device__ __forceinline__ unsigned cvt_pk_bf16(float lo, float hi) { unsigned r; asm volatile("v_cvt_pk_bf16_f32 %0, %1, %2" : "=v"(r) : "v"(lo), "v"(hi)); return r; }
;     __device__ __forceinline__ void operator()(const f32x4 (&acc)[2][2][4][2], const Unit& u, int wr, int wc, int fr, int fq, LAS unsigned char* lds) const {
;     ...
;             for (int m = 0; m < 4; ++m) { const size_t ro = (size_t)(row0 + ai * HALF + m * 16) * ldc + col0; float ssq = 0.f;
; #pragma unroll
;                 for (int bj = 0; bj < 2; ++bj) { const size_t o = ro + bj * HALF;
;                     const f32x4 r0 = *(const f32x4*)(res + o), r1 = *(const f32x4*)(res + o + 4);
;                     const f32x4 x0 = r0 + acc[ai][bj][m][0], x1 = r1 + acc[ai][bj][m][1];
;                     *(f32x4*)(O + o) = x0; *(f32x4*)(O + o + 4) = x1;
;                     u32x4 hb; hb.x = cvt_pk_bf16(x0[0] * gg[bj][0][0], x0[1] * gg[bj][0][1]); hb.y = cvt_pk_bf16(x0[2] * gg[bj][0][2], x0[3] * gg[bj][0][3]);
;                     hb.z = cvt_pk_bf16(x1[0] * gg[bj][1][0], x1[1] * gg[bj][1][1]); hb.w = cvt_pk_bf16(x1[2] * gg[bj][1][2], x1[3] * gg[bj][1][3]);
;                     *(u32x4*)(H + o) = hb;
;                     ssq += ((x0[0] * x0[0] + x0[1] * x0[1]) + (x0[2] * x0[2] + x0[3] * x0[3])) + ((x1[0] * x1[0] + x1[1] * x1[1]) + (x1[2] * x1[2] + x1[3] * x1[3])); }
;                 ssq += __shfl_xor(ssq, 16); ssq += __shfl_xor(ssq, 32);
;                 if (fq == 0) part[(ai * HALF + wr * 64 + m * 16 + fr) * 4 + wc] = ssq; }
	v_add_f32_e32 v27, v27, v29
	ds_bpermute_b32 v29, v55, v27
	s_waitcnt lgkmcnt(0)
	v_add_f32_e32 v27, v27, v29
	s_and_saveexec_b64 s[14:15], s[42:43]
	ds_write_b32 v176, v27 offset:2048
	s_or_b64 exec, exec, s[14:15]
	v_add_u32_e32 v177, 0x10000, v177
	v_add_u32_e32 v195, 0x10000, v195
	v_add_u32_e32 v247, 0x8000, v247
	v_add_u32_e32 v24, 0x8000, v24
	s_waitcnt vmcnt(28)
	v_pk_add_f32 v[60:61], v[60:61], v[228:229]
	v_pk_add_f32 v[62:63], v[62:63], v[230:231]
	v_pk_add_f32 v[44:45], v[44:45], v[232:233]
	v_pk_add_f32 v[46:47], v[46:47], v[234:235]
	v_pk_add_f32 v[56:57], v[56:57], v[236:237]
	v_pk_add_f32 v[58:59], v[58:59], v[238:239]
	v_pk_add_f32 v[40:41], v[40:41], v[240:241]
	v_pk_add_f32 v[42:43], v[42:43], v[242:243]
	global_store_dwordx4 v177, v[60:63], s[76:77]
	global_store_dwordx4 v177, v[44:47], s[76:77] offset:512
	global_store_dwordx4 v195, v[56:59], s[76:77]
	global_store_dwordx4 v195, v[40:43], s[76:77] offset:512
	v_mul_f32_e32 v27, v180, v60
	v_mul_f32_e32 v28, v181, v61
	v_cvt_pk_bf16_f32 v30, v27, v28
	v_mul_f32_e32 v27, v182, v62
	v_mul_f32_e32 v28, v183, v63
	v_cvt_pk_bf16_f32 v31, v27, v28
	global_store_dwordx2 v247, v[30:31], s[88:89]
	v_mul_f32_e32 v27, v166, v44
	v_mul_f32_e32 v28, v167, v45
	v_cvt_pk_bf16_f32 v48, v27, v28
	v_mul_f32_e32 v27, v168, v46
	v_mul_f32_e32 v28, v169, v47
	v_cvt_pk_bf16_f32 v49, v27, v28
	global_store_dwordx2 v247, v[48:49], s[88:89] offset:256
	v_mul_f32_e32 v27, v180, v56
	v_mul_f32_e32 v28, v181, v57
	v_cvt_pk_bf16_f32 v30, v27, v28
	v_mul_f32_e32 v27, v182, v58
	v_mul_f32_e32 v28, v183, v59
	v_cvt_pk_bf16_f32 v31, v27, v28
	global_store_dwordx2 v24, v[30:31], s[88:89]
	v_mul_f32_e32 v27, v166, v40
	v_mul_f32_e32 v28, v167, v41
	v_cvt_pk_bf16_f32 v48, v27, v28
	v_mul_f32_e32 v27, v168, v42
	v_mul_f32_e32 v28, v169, v43
	v_cvt_pk_bf16_f32 v49, v27, v28
	global_store_dwordx2 v24, v[48:49], s[88:89] offset:256
	v_mul_f32_e32 v50, v61, v61
	v_mul_f32_e32 v29, v63, v63
	v_fmac_f32_e32 v50, v60, v60
	v_fmac_f32_e32 v29, v62, v62
	v_add_f32_e32 v50, v50, v29
	v_mul_f32_e32 v51, v57, v57
	v_mul_f32_e32 v29, v59, v59
	v_fmac_f32_e32 v51, v56, v56
	v_fmac_f32_e32 v29, v58, v58
	v_add_f32_e32 v51, v51, v29
	v_mul_f32_e32 v52, v45, v45
	v_mul_f32_e32 v29, v47, v47
	v_fmac_f32_e32 v52, v44, v44
	v_fmac_f32_e32 v29, v46, v46
	v_add_f32_e32 v52, v52, v29
	v_mul_f32_e32 v53, v41, v41
	v_mul_f32_e32 v29, v43, v43
	v_fmac_f32_e32 v53, v40, v40
	v_fmac_f32_e32 v29, v42, v42
	v_add_f32_e32 v53, v53, v29
	v_add_f32_dpp v27, v50, v50 row_ror:8 row_mask:0xf bank_mask:0x3
	v_add_f32_dpp v28, v52, v52 row_ror:8 row_mask:0xf bank_mask:0x3
	v_add_f32_dpp v27, v51, v51 row_ror:8 row_mask:0xf bank_mask:0xc
	v_add_f32_dpp v28, v53, v53 row_ror:8 row_mask:0xf bank_mask:0xc
	v_add_f32_e32 v27, v27, v28
	ds_bpermute_b32 v29, v54, v27
	s_waitcnt lgkmcnt(0)
	v_add_f32_e32 v27, v27, v29
	ds_bpermute_b32 v29, v55, v27
	s_waitcnt lgkmcnt(0)
	v_add_f32_e32 v27, v27, v29
	s_and_saveexec_b64 s[14:15], s[42:43]
	ds_write_b32 v176, v27 offset:2304
	s_or_b64 exec, exec, s[14:15]
	v_add_u32_e32 v177, 0x10000, v177
	v_add_u32_e32 v195, 0x10000, v195
	v_add_u32_e32 v247, 0x8000, v247
	v_add_u32_e32 v24, 0x8000, v24
	s_waitcnt vmcnt(24)
	v_pk_add_f32 v[36:37], v[36:37], v[196:197]
	v_pk_add_f32 v[38:39], v[38:39], v[198:199]
	v_pk_add_f32 v[20:21], v[20:21], v[200:201]
	v_pk_add_f32 v[22:23], v[22:23], v[202:203]
	v_pk_add_f32 v[32:33], v[32:33], v[204:205]
	v_pk_add_f32 v[34:35], v[34:35], v[206:207]
	v_pk_add_f32 v[16:17], v[16:17], v[208:209]
	v_pk_add_f32 v[18:19], v[18:19], v[210:211]
	global_store_dwordx4 v177, v[36:39], s[76:77]
	global_store_dwordx4 v177, v[20:23], s[76:77] offset:512
	global_store_dwordx4 v195, v[32:35], s[76:77]
	global_store_dwordx4 v195, v[16:19], s[76:77] offset:512
	v_mul_f32_e32 v27, v180, v36
	v_mul_f32_e32 v28, v181, v37
	v_cvt_pk_bf16_f32 v30, v27, v28
	v_mul_f32_e32 v27, v182, v38
	v_mul_f32_e32 v28, v183, v39
	v_cvt_pk_bf16_f32 v31, v27, v28
	global_store_dwordx2 v247, v[30:31], s[88:89]
	v_mul_f32_e32 v27, v166, v20
	v_mul_f32_e32 v28, v167, v21
	v_cvt_pk_bf16_f32 v48, v27, v28
	v_mul_f32_e32 v27, v168, v22
	v_mul_f32_e32 v28, v169, v23
	v_cvt_pk_bf16_f32 v49, v27, v28
	global_store_dwordx2 v247, v[48:49], s[88:89] offset:256
	v_mul_f32_e32 v27, v180, v32
	v_mul_f32_e32 v28, v181, v33
	v_cvt_pk_bf16_f32 v30, v27, v28
	v_mul_f32_e32 v27, v182, v34
	v_mul_f32_e32 v28, v183, v35
	v_cvt_pk_bf16_f32 v31, v27, v28
	global_store_dwordx2 v24, v[30:31], s[88:89]
	v_mul_f32_e32 v27, v166, v16
	v_mul_f32_e32 v28, v167, v17
	v_cvt_pk_bf16_f32 v48, v27, v28
	v_mul_f32_e32 v27, v168, v18
	v_mul_f32_e32 v28, v169, v19
	v_cvt_pk_bf16_f32 v49, v27, v28
	global_store_dwordx2 v24, v[48:49], s[88:89] offset:256
	v_mul_f32_e32 v50, v37, v37
	v_mul_f32_e32 v29, v39, v39
	v_fmac_f32_e32 v50, v36, v36
	v_fmac_f32_e32 v29, v38, v38
	v_add_f32_e32 v50, v50, v29
	v_mul_f32_e32 v51, v33, v33
	v_mul_f32_e32 v29, v35, v35
	v_fmac_f32_e32 v51, v32, v32
	v_fmac_f32_e32 v29, v34, v34
	v_add_f32_e32 v51, v51, v29
	v_mul_f32_e32 v52, v21, v21
	v_mul_f32_e32 v29, v23, v23
	v_fmac_f32_e32 v52, v20, v20
	v_fmac_f32_e32 v29, v22, v22
	v_add_f32_e32 v52, v52, v29
	v_mul_f32_e32 v53, v17, v17
	v_mul_f32_e32 v29, v19, v19
	v_fmac_f32_e32 v53, v16, v16
	v_fmac_f32_e32 v29, v18, v18
	v_add_f32_e32 v53, v53, v29
	v_add_f32_dpp v27, v50, v50 row_ror:8 row_mask:0xf bank_mask:0x3
	v_add_f32_dpp v28, v52, v52 row_ror:8 row_mask:0xf bank_mask:0x3
	v_add_f32_dpp v27, v51, v51 row_ror:8 row_mask:0xf bank_mask:0xc
	v_add_f32_dpp v28, v53, v53 row_ror:8 row_mask:0xf bank_mask:0xc
	v_add_f32_e32 v27, v27, v28
	ds_bpermute_b32 v29, v54, v27
	s_waitcnt lgkmcnt(0)
; #define LAS __attribute__((address_space(3)))
; __device__ __forceinline__ unsigned cvt_pk_bf16(float lo, float hi) { unsigned r; asm volatile("v_cvt_pk_bf16_f32 %0, %1, %2" : "=v"(r) : "v"(lo), "v"(hi)); return r; }
;     __device__ __forceinline__ void operator()(const f32x4 (&acc)[2][2][4][2], const Unit& u, int wr, int wc, int fr, int fq, LAS unsigned char* lds) const {
;     ...
;             for (int m = 0; m < 4; ++m) { const size_t ro = (size_t)(row0 + ai * HALF + m * 16) * ldc + col0; float ssq = 0.f;
; #pragma unroll
;                 for (int bj = 0; bj < 2; ++bj) { const size_t o = ro + bj * HALF;
;                     const f32x4 r0 = *(const f32x4*)(res + o), r1 = *(const f32x4*)(res + o + 4);
;                     const f32x4 x0 = r0 + acc[ai][bj][m][0], x1 = r1 + acc[ai][bj][m][1];
;                     *(f32x4*)(O + o) = x0; *(f32x4*)(O + o + 4) = x1;
;                     u32x4 hb; hb.x = cvt_pk_bf16(x0[0] * gg[bj][0][0], x0[1] * gg[bj][0][1]); hb.y = cvt_pk_bf16(x0[2] * gg[bj][0][2], x0[3] * gg[bj][0][3]);
;                     hb.z = cvt_pk_bf16(x1[0] * gg[bj][1][0], x1[1] * gg[bj][1][1]); hb.w = cvt_pk_bf16(x1[2] * gg[bj][1][2], x1[3] * gg[bj][1][3]);
;                     *(u32x4*)(H + o) = hb;
;                     ssq += ((x0[0] * x0[0] + x0[1] * x0[1]) + (x0[2] * x0[2] + x0[3] * x0[3])) + ((x1[0] * x1[0] + x1[1] * x1[1]) + (x1[2] * x1[2] + x1[3] * x1[3])); }
;                 ssq += __shfl_xor(ssq, 16); ssq += __shfl_xor(ssq, 32);
;                 if (fq == 0) part[(ai * HALF + wr * 64 + m * 16 + fr) * 4 + wc] = ssq; }
;         asm volatile("s_waitcnt lgkmcnt(0)" ::: "memory"); __builtin_amdgcn_s_barrier(); asm volatile("" ::: "memory");
;         const int t = threadIdx.x;
;         if (t < 256) { const f32x4 p = *(const LAS f32x4*)(part + t * 4); rss[(size_t)u.pn * NTOK + u.pm * BM + t] = (p[0] + p[1]) + (p[2] + p[3]); }
	v_add_f32_e32 v27, v27, v29
	ds_bpermute_b32 v29, v55, v27
	s_waitcnt lgkmcnt(0)
	v_add_f32_e32 v27, v27, v29
	s_and_saveexec_b64 s[14:15], s[42:43]
	ds_write_b32 v176, v27 offset:2560
	s_or_b64 exec, exec, s[14:15]
	v_add_u32_e32 v177, 0x10000, v177
	v_add_u32_e32 v195, 0x10000, v195
	v_add_u32_e32 v247, 0x8000, v247
	v_add_u32_e32 v24, 0x8000, v24
	s_waitcnt vmcnt(20)
	v_pk_add_f32 v[12:13], v[12:13], v[212:213]
	v_pk_add_f32 v[14:15], v[14:15], v[214:215]
	v_pk_add_f32 v[4:5], v[4:5], v[216:217]
	v_pk_add_f32 v[6:7], v[6:7], v[218:219]
	v_pk_add_f32 v[8:9], v[8:9], v[220:221]
	v_pk_add_f32 v[10:11], v[10:11], v[222:223]
	v_pk_add_f32 v[0:1], v[0:1], v[224:225]
	v_pk_add_f32 v[2:3], v[2:3], v[226:227]
	global_store_dwordx4 v177, v[12:15], s[76:77]
	global_store_dwordx4 v177, v[4:7], s[76:77] offset:512
	global_store_dwordx4 v195, v[8:11], s[76:77]
	global_store_dwordx4 v195, v[0:3], s[76:77] offset:512
	v_mul_f32_e32 v27, v180, v12
	v_mul_f32_e32 v28, v181, v13
	v_cvt_pk_bf16_f32 v30, v27, v28
	v_mul_f32_e32 v27, v182, v14
	v_mul_f32_e32 v28, v183, v15
	v_cvt_pk_bf16_f32 v31, v27, v28
	global_store_dwordx2 v247, v[30:31], s[88:89]
	v_mul_f32_e32 v27, v166, v4
	v_mul_f32_e32 v28, v167, v5
	v_cvt_pk_bf16_f32 v48, v27, v28
	v_mul_f32_e32 v27, v168, v6
	v_mul_f32_e32 v28, v169, v7
	v_cvt_pk_bf16_f32 v49, v27, v28
	global_store_dwordx2 v247, v[48:49], s[88:89] offset:256
	v_mul_f32_e32 v27, v180, v8
	v_mul_f32_e32 v28, v181, v9
	v_cvt_pk_bf16_f32 v30, v27, v28
	v_mul_f32_e32 v27, v182, v10
	v_mul_f32_e32 v28, v183, v11
	v_cvt_pk_bf16_f32 v31, v27, v28
	global_store_dwordx2 v24, v[30:31], s[88:89]
	v_mul_f32_e32 v27, v166, v0
	v_mul_f32_e32 v28, v167, v1
	v_cvt_pk_bf16_f32 v48, v27, v28
	v_mul_f32_e32 v27, v168, v2
	v_mul_f32_e32 v28, v169, v3
	v_cvt_pk_bf16_f32 v49, v27, v28
	global_store_dwordx2 v24, v[48:49], s[88:89] offset:256
	v_mul_f32_e32 v50, v13, v13
	v_mul_f32_e32 v29, v15, v15
	v_fmac_f32_e32 v50, v12, v12
	v_fmac_f32_e32 v29, v14, v14
	v_add_f32_e32 v50, v50, v29
	v_mul_f32_e32 v51, v9, v9
	v_mul_f32_e32 v29, v11, v11
	v_fmac_f32_e32 v51, v8, v8
	v_fmac_f32_e32 v29, v10, v10
	v_add_f32_e32 v51, v51, v29
	v_mul_f32_e32 v52, v5, v5
	v_mul_f32_e32 v29, v7, v7
	v_fmac_f32_e32 v52, v4, v4
	v_fmac_f32_e32 v29, v6, v6
	v_add_f32_e32 v52, v52, v29
	v_mul_f32_e32 v53, v1, v1
	v_mul_f32_e32 v29, v3, v3
	v_fmac_f32_e32 v53, v0, v0
	v_fmac_f32_e32 v29, v2, v2
	v_add_f32_e32 v53, v53, v29
	v_add_f32_dpp v27, v50, v50 row_ror:8 row_mask:0xf bank_mask:0x3
	v_add_f32_dpp v28, v52, v52 row_ror:8 row_mask:0xf bank_mask:0x3
	v_add_f32_dpp v27, v51, v51 row_ror:8 row_mask:0xf bank_mask:0xc
	v_add_f32_dpp v28, v53, v53 row_ror:8 row_mask:0xf bank_mask:0xc
	v_add_f32_e32 v27, v27, v28
	ds_bpermute_b32 v29, v54, v27
	s_waitcnt lgkmcnt(0)
	v_add_f32_e32 v27, v27, v29
	ds_bpermute_b32 v29, v55, v27
	s_waitcnt lgkmcnt(0)
	v_add_f32_e32 v27, v27, v29
	s_and_saveexec_b64 s[14:15], s[42:43]
	ds_write_b32 v176, v27 offset:2816
	s_or_b64 exec, exec, s[14:15]
	s_waitcnt lgkmcnt(0)
	s_barrier
	s_mov_b64 s[14:15], exec
	v_readlane_b32 s4, v246, 6
	v_readlane_b32 s5, v246, 7
	s_and_b64 s[4:5], s[14:15], s[4:5]
	s_mov_b64 exec, s[4:5]
	s_cbranch_execz .LBB0_804
	s_waitcnt lgkmcnt(0)
	ds_read_b128 v[0:3], v189
	s_ashr_i32 s57, s56, 31
	s_ashr_i32 s47, s46, 31
	s_lshl_b64 s[4:5], s[56:57], 16
	v_readlane_b32 s16, v246, 4
	v_readlane_b32 s17, v246, 5
	s_add_u32 s16, s16, s4
	s_addc_u32 s17, s17, s5
	s_lshl_b64 s[4:5], s[46:47], 2
	s_waitcnt lgkmcnt(0)
	v_mov_b32_e32 v4, v1
	v_mov_b32_e32 v5, v2
	v_mov_b32_e32 v1, v3
	s_add_u32 s4, s16, s4
	v_pk_add_f32 v[0:1], v[4:5], v[0:1]
	s_addc_u32 s5, s17, s5
	v_add_f32_e32 v2, v0, v1
	v_lshl_add_u64 v[0:1], v[178:179], 2, s[4:5]
	global_store_dword v[0:1], v2, off

; __device__ __forceinline__ unsigned xb_ld(unsigned* p)              { return __hip_atomic_load(p, __ATOMIC_RELAXED, __HIP_MEMORY_SCOPE_AGENT); }
; __device__ __forceinline__ unsigned xb_add(unsigned* p, unsigned v) { return __hip_atomic_fetch_add(p, v, __ATOMIC_RELAXED, __HIP_MEMORY_SCOPE_AGENT); }
; #define XB_SPIN(cond, bar) do { unsigned _sp = 0; while (cond) { __builtin_amdgcn_s_sleep(1); \
;     if ((++_sp & 255u) == 0u) { if (xb_ld(&(bar)[XB_TMO])) break; if (_sp > XB_SPIN_CAP) { atomicAdd(&(bar)[XB_TMO], 1u); break; } } } } while (0)
; __device__ __forceinline__ void xcd_barrier(const XcdBarrier& b) {
;     asm volatile("s_waitcnt vmcnt(0)" ::: "memory");
;     __syncthreads();
;     if (threadIdx.x == 0) {
;         unsigned* bar = b.bar;
;         __builtin_amdgcn_s_waitcnt(0);
;         unsigned nloc = b.st[0], nx = b.st[1];
;         if (nloc == 0u) { xcd_barrier_complete(bar, b.x, nloc, nx); b.st[0] = nloc; b.st[1] = nx; }
;         const unsigned old = xb_add(&bar[XB_XSUB(b.x)], 1u);
;         const unsigned gen = old / nloc;
;         if (old + 1u == (gen + 1u) * nloc) {
;             __builtin_amdgcn_fence(__ATOMIC_RELEASE, "agent");
;             asm volatile("s_waitcnt vmcnt(0)" ::: "memory");
;             const unsigned og = xb_add(&bar[XB_TOP], 1u);
;             const unsigned tg = og / nx;
;             if (og + 1u == (tg + 1u) * nx) xb_add(&bar[XB_TOPGEN], 1u);
;             else XB_SPIN(xb_ld(&bar[XB_TOPGEN]) == tg, bar);
;             __builtin_amdgcn_fence(__ATOMIC_ACQUIRE, "agent");
;             xb_add(&bar[XB_XGEN(b.x)], 1u);
;             asm volatile("s_waitcnt vmcnt(0)" ::: "memory");
;         } else {
;             XB_SPIN(xb_ld(&bar[XB_XGEN(b.x)]) == gen, bar);
;             __builtin_amdgcn_fence(__ATOMIC_ACQUIRE, "agent");
;             asm volatile("s_waitcnt vmcnt(0)" ::: "memory");
;         }
;     }
;     __syncthreads();
; }
.Lbbsb:
	s_setprio 0
	s_waitcnt vmcnt(0) lgkmcnt(0)
	s_barrier
	s_add_u32 s8, s78, 0xfc00000
	s_addc_u32 s9, s79, 0
	s_and_b32 s5, s2, 7
	s_lshl_b32 s5, s5, 6
	s_add_i32 s101, s101, 1
	s_and_b32 s6, s101, 0xffff
	s_lshl_b32 s6, s6, 5
	v_cmp_eq_u32_e32 vcc, 0, v178
	s_and_saveexec_b64 s[14:15], vcc
	s_cbranch_execz .Lbbsb_join
	v_mov_b32_e32 v0, s5
	v_mov_b32_e32 v2, 1
	s_cmp_lg_u32 s100, 0
	s_cbranch_scc1 .Lbbsb_known
	global_load_dword v1, v0, s[8:9] offset:32 sc1
	s_waitcnt vmcnt(0)
	v_readfirstlane_b32 s16, v1
	s_bcnt1_i32_b32 s16, s16
	s_cmp_eq_u32 s16, 1
	s_cselect_b32 s100, 1, 2

; __device__ __forceinline__ unsigned xb_ld(unsigned* p)              { return __hip_atomic_load(p, __ATOMIC_RELAXED, __HIP_MEMORY_SCOPE_AGENT); }
; __device__ __forceinline__ unsigned xb_add(unsigned* p, unsigned v) { return __hip_atomic_fetch_add(p, v, __ATOMIC_RELAXED, __HIP_MEMORY_SCOPE_AGENT); }
; #define XB_SPIN(cond, bar) do { unsigned _sp = 0; while (cond) { __builtin_amdgcn_s_sleep(1); \
;     if ((++_sp & 255u) == 0u) { if (xb_ld(&(bar)[XB_TMO])) break; if (_sp > XB_SPIN_CAP) { atomicAdd(&(bar)[XB_TMO], 1u); break; } } } } while (0)
; __device__ __forceinline__ void xcd_barrier(const XcdBarrier& b) {
;     asm volatile("s_waitcnt vmcnt(0)" ::: "memory");
;     __syncthreads();
;     if (threadIdx.x == 0) {
;         unsigned* bar = b.bar;
;         __builtin_amdgcn_s_waitcnt(0);
;         unsigned nloc = b.st[0], nx = b.st[1];
;         if (nloc == 0u) { xcd_barrier_complete(bar, b.x, nloc, nx); b.st[0] = nloc; b.st[1] = nx; }
;         const unsigned old = xb_add(&bar[XB_XSUB(b.x)], 1u);
;         const unsigned gen = old / nloc;
;         if (old + 1u == (gen + 1u) * nloc) {
;             __builtin_amdgcn_fence(__ATOMIC_RELEASE, "agent");
;             asm volatile("s_waitcnt vmcnt(0)" ::: "memory");
;             const unsigned og = xb_add(&bar[XB_TOP], 1u);
;             const unsigned tg = og / nx;
;             if (og + 1u == (tg + 1u) * nx) xb_add(&bar[XB_TOPGEN], 1u);
;             else XB_SPIN(xb_ld(&bar[XB_TOPGEN]) == tg, bar);
;             __builtin_amdgcn_fence(__ATOMIC_ACQUIRE, "agent");
;             xb_add(&bar[XB_XGEN(b.x)], 1u);
;             asm volatile("s_waitcnt vmcnt(0)" ::: "memory");
;         } else {
;             XB_SPIN(xb_ld(&bar[XB_XGEN(b.x)]) == gen, bar);
;             __builtin_amdgcn_fence(__ATOMIC_ACQUIRE, "agent");
;             asm volatile("s_waitcnt vmcnt(0)" ::: "memory");
;         }
;     }
;     __syncthreads();
; }
.Lpbsb4:
	s_setprio 0
	s_waitcnt vmcnt(0) lgkmcnt(0)
	s_barrier
	s_add_u32 s8, s78, 0xfc00000
	s_addc_u32 s9, s79, 0
	s_and_b32 s5, s2, 7
	s_lshl_b32 s5, s5, 3
	s_bfe_u32 s6, s2, 0x30003
	s_or_b32 s5, s5, s6
	s_lshl_b32 s5, s5, 2
	s_add_i32 s5, s5, 640
	s_add_i32 s101, s101, 0x10000
	s_lshr_b32 s6, s101, 16
	s_lshl_b32 s6, s6, 2
	v_cmp_eq_u32_e32 vcc, 0, v178
	s_and_saveexec_b64 s[14:15], vcc
	s_cbranch_execz .Lpbsb4_join
	v_mov_b32_e32 v0, s5
	v_mov_b32_e32 v2, 1
	s_cmp_eq_u32 s100, 1
	s_cbranch_scc1 .Lpbsb4_fast
	buffer_wbl2 sc1
	s_waitcnt vmcnt(0)

; __device__ __forceinline__ unsigned xb_ld(unsigned* p)              { return __hip_atomic_load(p, __ATOMIC_RELAXED, __HIP_MEMORY_SCOPE_AGENT); }
; __device__ __forceinline__ unsigned xb_add(unsigned* p, unsigned v) { return __hip_atomic_fetch_add(p, v, __ATOMIC_RELAXED, __HIP_MEMORY_SCOPE_AGENT); }
; #define XB_SPIN(cond, bar) do { unsigned _sp = 0; while (cond) { __builtin_amdgcn_s_sleep(1); \
;     if ((++_sp & 255u) == 0u) { if (xb_ld(&(bar)[XB_TMO])) break; if (_sp > XB_SPIN_CAP) { atomicAdd(&(bar)[XB_TMO], 1u); break; } } } } while (0)
; __device__ __forceinline__ void xcd_barrier(const XcdBarrier& b) {
;     ...
;         const unsigned old = xb_add(&bar[XB_XSUB(b.x)], 1u);
;         const unsigned gen = old / nloc;
;         if (old + 1u == (gen + 1u) * nloc) {
;             __builtin_amdgcn_fence(__ATOMIC_RELEASE, "agent");
;             asm volatile("s_waitcnt vmcnt(0)" ::: "memory");
;             const unsigned og = xb_add(&bar[XB_TOP], 1u);
;             const unsigned tg = og / nx;
;             if (og + 1u == (tg + 1u) * nx) xb_add(&bar[XB_TOPGEN], 1u);
;             else XB_SPIN(xb_ld(&bar[XB_TOPGEN]) == tg, bar);
;             __builtin_amdgcn_fence(__ATOMIC_ACQUIRE, "agent");
;             xb_add(&bar[XB_XGEN(b.x)], 1u);
.Lpbsb3_fast:
	global_atomic_add v0, v2, s[8:9]
	s_and_b32 s16, s2, 7
	s_lshl_b32 s16, s16, 6
	v_mov_b32_e32 v1, s16
	global_atomic_add v1, v2, s[8:9] offset:8
	s_cmp_eq_u32 s100, 1
	s_cbranch_scc0 .Lpbsb3_noearly
	buffer_inv sc1
